# adds pp_row next-row L2 touch-prefetch on top of G2 rope LDS table and G4/G6 resid epilogue load-batching
# speedup vs baseline: 1.0161x; 1.0000x over previous
.LBB0_1617:
	s_or_b64 exec, exec, s[6:7]
	v_lshl_or_b32 v98, v29, 1, s22
	v_ashrrev_i32_e32 v99, 31, v98
	v_lshlrev_b64 v[98:99], 8, v[98:99]
	v_lshl_add_u64 v[98:99], v[98:99], 0, v[128:129]
	s_waitcnt vmcnt(0)
	v_lshlrev_b32_e32 v248, 6, v226
	v_mov_b32_e32 v249, 0
	v_lshl_add_u64 v[246:247], v[76:77], 0, s[96:97]
	v_lshl_add_u64 v[246:247], v[246:247], 0, v[248:249]
	global_load_dword v245, v[246:247], off offset:-2048
	v_lshlrev_b32_e32 v116, 16, v20
	v_and_b32_e32 v117, 0xffff0000, v20
	v_lshlrev_b32_e32 v118, 16, v21
	v_and_b32_e32 v119, 0xffff0000, v21
	v_lshlrev_b32_e32 v20, 16, v22
	v_and_b32_e32 v21, 0xffff0000, v22
	v_lshlrev_b32_e32 v22, 16, v23
	v_and_b32_e32 v23, 0xffff0000, v23
	s_and_saveexec_b64 s[6:7], s[52:53]
	s_xor_b64 s[6:7], exec, s[6:7]
	s_cbranch_execz .LBB0_1623
	v_lshlrev_b32_e32 v124, 16, v114
	v_and_b32_e32 v125, 0xffff0000, v114
	v_lshlrev_b32_e32 v126, 16, v115
	v_and_b32_e32 v127, 0xffff0000, v115
	v_lshlrev_b64 v[114:115], 10, v[98:99]
	v_lshl_add_u64 v[130:131], v[60:61], 0, v[114:115]
	v_lshl_add_u64 v[114:115], v[62:63], 0, v[114:115]
	global_store_dwordx4 v[130:131], v[20:23], off
	global_store_dwordx4 v[114:115], v[124:127], off
	s_and_saveexec_b64 s[8:9], s[0:1]
	s_cbranch_execz .LBB0_1620
	v_lshlrev_b64 v[114:115], 9, v[98:99]
	v_lshl_add_u64 v[114:115], v[64:65], 0, v[114:115]
	global_store_dwordx4 v[114:115], v[24:27], off
